# branch-GEMM epilogue: the per-tile f32 gated partial sum (tmp) now uses a workgroup-private lane-contiguous layout so each x4 load/store is one contiguous 1 KiB burst instead of sixteen 16-byte pieces
# speedup vs baseline: 1.0053x; 1.0053x over previous
; __device__ __forceinline__ unsigned cvt_pk_bf16(float lo, float hi) { unsigned r; asm("v_cvt_pk_bf16_f32 %0, %1, %2" : "=v"(r) : "v"(lo), "v"(hi)); return r; }
; __device__ __forceinline__ float sigm(float x) { return rcpf_(1.f + __expf(-x)); }
; __device__ __forceinline__ void unpack8(u32x4 w, float* e) { e[0] = lo_bf(w.x); e[1] = hi_bf(w.x); e[2] = lo_bf(w.y); e[3] = hi_bf(w.y); e[4] = lo_bf(w.z); e[5] = hi_bf(w.z); e[6] = lo_bf(w.w); e[7] = hi_bf(w.w); }
;     __device__ __forceinline__ void operator()(const f32x4 (&acc)[2][2][4][2], const Unit& u, int wr, int wc, int fr, int fq) const {
;         const int row0 = u.pm * 256 + wr * 64 + fr, colt = u.pn * 256 + wc * 32 + 8 * fq;
; #pragma unroll
;         for (int ai = 0; ai < 2; ++ai)
; #pragma unroll
;             for (int m = 0; m < 4; ++m) {
;                 const int row = row0 + ai * 128 + m * 16;
; #pragma unroll
;                 for (int bj = 0; bj < 2; ++bj) {
;                     const int col = colt + bj * 128;
;                     const u32x4 gw = *(const u32x4*)(P + (size_t)row * NIN + C_GM + u.z * 1024 + col);
;                     float gt[8]; unpack8(gw, gt);
;                     f32x4 v0 = acc[ai][bj][m][0], v1 = acc[ai][bj][m][1];
; #pragma unroll
;                     for (int j = 0; j < 4; ++j) { v0[j] *= sigm(gt[j]); v1[j] *= sigm(gt[4 + j]); }
;                     float* tp = tmp + (size_t)row * 1024 + col;
;                     if (u.z > 0) { v0 += *(const f32x4*)tp; v1 += *(const f32x4*)(tp + 4); }
;                     if (u.z < 2) { *(f32x4*)tp = v0; *(f32x4*)(tp + 4) = v1; }
;                     else { u32x4 w; w.x = cvt_pk_bf16(v0[0], v0[1]); w.y = cvt_pk_bf16(v0[2], v0[3]); w.z = cvt_pk_bf16(v1[0], v1[1]); w.w = cvt_pk_bf16(v1[2], v1[3]);
;                         *(u32x4*)(merged + (size_t)row * 1024 + col) = w; }
.LBB0_116:
	s_lshl_b32 s98, s87, 2
	s_add_i32 s98, s98, s86
	s_lshl_b32 s98, s98, 3
	v_lshrrev_b32_e32 v252, 6, v234
	v_add_u32_e32 v252, s98, v252
	v_lshlrev_b32_e32 v252, 15, v252
	v_and_b32_e32 v253, 63, v234
	v_lshl_add_u32 v252, v253, 4, v252
	v_mov_b32_e32 v253, 0
	v_lshl_add_u64 v[252:253], v[252:253], 0, s[16:17]
	v_lshl_add_u32 v142, s87, 8, v150
	v_mov_b64_e32 v[144:145], s[12:13]
	s_lshl_b32 s38, s85, 10
	v_lshl_or_b32 v140, s86, 8, v152
	v_mad_i64_i32 v[144:145], s[6:7], v142, s43, v[144:145]
	s_ashr_i32 s39, s38, 31
	v_lshl_add_u64 v[144:145], s[38:39], 1, v[144:145]
	v_ashrrev_i32_e32 v141, 31, v140
	v_lshl_add_u64 v[144:145], v[140:141], 1, v[144:145]
	v_add_co_u32_e32 v146, vcc, 0x4000, v144
	v_ashrrev_i32_e32 v143, 31, v142
	s_nop 0
	v_addc_co_u32_e32 v147, vcc, 0, v145, vcc
	global_load_dwordx4 v[196:199], v[146:147], off offset:256
	s_mov_b32 s99, 0
	s_mov_b32 s98, 0x58000
	v_lshl_add_u64 v[162:163], v[146:147], 0, s[98:99]
	global_load_dwordx4 v[200:203], v[162:163], off offset:256
	global_load_dwordx4 v[162:165], v[162:163], off
	s_mov_b32 s98, 0xb0000
	v_lshl_add_u64 v[166:167], v[146:147], 0, s[98:99]
	global_load_dwordx4 v[204:207], v[166:167], off offset:256
	global_load_dwordx4 v[166:169], v[166:167], off
	s_mov_b32 s98, 0x108000
	v_lshl_add_u64 v[170:171], v[146:147], 0, s[98:99]
	global_load_dwordx4 v[208:211], v[170:171], off offset:256
	global_load_dwordx4 v[170:173], v[170:171], off
	s_mov_b32 s98, 0x2c0000
	v_lshl_add_u64 v[174:175], v[146:147], 0, s[98:99]
	global_load_dwordx4 v[212:215], v[174:175], off offset:256
	global_load_dwordx4 v[174:177], v[174:175], off
	s_mov_b32 s98, 0x318000
	v_lshl_add_u64 v[178:179], v[146:147], 0, s[98:99]
	global_load_dwordx4 v[230:233], v[178:179], off offset:256
	global_load_dwordx4 v[178:181], v[178:179], off
	s_mov_b32 s98, 0x370000
	v_lshl_add_u64 v[188:189], v[146:147], 0, s[98:99]
	global_load_dwordx4 v[248:251], v[188:189], off offset:256
	global_load_dwordx4 v[188:191], v[188:189], off
	s_mov_b32 s98, 0x3c8000
	v_lshl_add_u64 v[192:193], v[146:147], 0, s[98:99]
	global_load_dwordx4 v[192:195], v[192:193], off
	s_mov_b32 s98, 0x800
	global_load_dwordx4 v[146:149], v[146:147], off
	s_cmp_gt_i32 s85, 0
	s_cselect_b64 s[8:9], -1, 0
	s_cmp_lt_i32 s85, 1
	s_waitcnt vmcnt(0)
	v_lshlrev_b32_e32 v156, 16, v147
	v_and_b32_e32 v157, 0xffff0000, v147
	v_lshlrev_b32_e32 v147, 16, v148
	v_mul_f32_e32 v147, 0xbfb8aa3b, v147
	v_exp_f32_e32 v147, v147
	v_lshlrev_b32_e32 v154, 16, v146
	v_and_b32_e32 v155, 0xffff0000, v146
	v_and_b32_e32 v158, 0xffff0000, v148
	v_add_f32_e32 v147, 1.0, v147
	v_mul_f32_e32 v146, 0xbfb8aa3b, v154
	v_rcp_f32_e32 v148, v147
	v_mul_f32_e32 v147, 0xbfb8aa3b, v155
	v_exp_f32_e32 v146, v146
	v_exp_f32_e32 v147, v147
	v_lshlrev_b32_e32 v159, 16, v149
	v_mul_f32_e32 v155, 0xbfb8aa3b, v159
	v_add_f32_e32 v146, 1.0, v146
	v_add_f32_e32 v147, 1.0, v147
	v_exp_f32_e32 v155, v155
	v_rcp_f32_e32 v146, v146
	v_rcp_f32_e32 v147, v147
	v_and_b32_e32 v160, 0xffff0000, v149
	v_add_f32_e32 v155, 1.0, v155
	v_mul_f32_e32 v149, 0xbfb8aa3b, v158
	v_mul_f32_e32 v154, 0xbfb8aa3b, v156
	v_rcp_f32_e32 v156, v155
	v_mul_f32_e32 v155, 0xbfb8aa3b, v157
	v_pk_mul_f32 v[126:127], v[126:127], v[146:147]
	v_mul_f32_e32 v146, 0xbfb8aa3b, v160
	v_exp_f32_e32 v149, v149
	v_exp_f32_e32 v154, v154
	v_exp_f32_e32 v155, v155
	v_exp_f32_e32 v146, v146
	v_add_f32_e32 v149, 1.0, v149
	v_add_f32_e32 v154, 1.0, v154
	v_add_f32_e32 v155, 1.0, v155
	v_add_f32_e32 v146, 1.0, v146
	v_rcp_f32_e32 v149, v149
	v_rcp_f32_e32 v154, v154
	v_rcp_f32_e32 v155, v155
	v_rcp_f32_e32 v157, v146
	v_lshlrev_b64 v[146:147], 12, v[142:143]
	v_lshl_add_u64 v[146:147], s[16:17], 0, v[146:147]
	v_pk_mul_f32 v[128:129], v[128:129], v[154:155]
	v_pk_mul_f32 v[124:125], v[124:125], v[156:157]
	v_pk_mul_f32 v[122:123], v[122:123], v[148:149]
	v_lshl_add_u64 v[146:147], v[140:141], 2, v[146:147]
	s_cbranch_scc1 .LBB0_118
	global_load_dwordx4 v[154:157], v[252:253], off
	global_load_dwordx4 v[158:161], v[252:253], off offset:1024
	s_waitcnt vmcnt(0)
	v_pk_add_f32 v[128:129], v[128:129], v[156:157]
	v_pk_add_f32 v[126:127], v[126:127], v[154:155]
	v_pk_add_f32 v[124:125], v[124:125], v[160:161]
	v_pk_add_f32 v[122:123], v[122:123], v[158:159]

; __device__ __forceinline__ float sigm(float x) { return rcpf_(1.f + __expf(-x)); }
; __device__ __forceinline__ void unpack8(u32x4 w, float* e) { e[0] = lo_bf(w.x); e[1] = hi_bf(w.x); e[2] = lo_bf(w.y); e[3] = hi_bf(w.y); e[4] = lo_bf(w.z); e[5] = hi_bf(w.z); e[6] = lo_bf(w.w); e[7] = hi_bf(w.w); }
;     __device__ __forceinline__ void operator()(const f32x4 (&acc)[2][2][4][2], const Unit& u, int wr, int wc, int fr, int fq) const {
;     ...
;                     const int col = colt + bj * 128;
;                     const u32x4 gw = *(const u32x4*)(P + (size_t)row * NIN + C_GM + u.z * 1024 + col);
;                     float gt[8]; unpack8(gw, gt);
;                     f32x4 v0 = acc[ai][bj][m][0], v1 = acc[ai][bj][m][1];
; #pragma unroll
;                     for (int j = 0; j < 4; ++j) { v0[j] *= sigm(gt[j]); v1[j] *= sigm(gt[4 + j]); }
;                     float* tp = tmp + (size_t)row * 1024 + col;
;                     if (u.z > 0) { v0 += *(const f32x4*)tp; v1 += *(const f32x4*)(tp + 4); }
;                     if (u.z < 2) { *(f32x4*)tp = v0; *(f32x4*)(tp + 4) = v1; }
.LBB0_120:
	s_andn2_b64 vcc, exec, s[6:7]
	s_cbranch_vccnz .LBB0_122
	global_store_dwordx4 v[252:253], v[126:129], off
	global_store_dwordx4 v[252:253], v[122:125], off offset:1024
.LBB0_122:
	s_mov_b64 s[6:7], 0x4000
	s_nop 0
	v_lshl_add_u64 v[122:123], v[144:145], 0, s[6:7]
	v_lshl_add_u64 v[252:253], v[252:253], 0, s[98:99]
	v_mov_b32_e32 v122, v196
	v_mov_b32_e32 v123, v197
	v_mov_b32_e32 v124, v198
	v_mov_b32_e32 v125, v199
	v_cndmask_b32_e64 v126, 0, 1, s[8:9]
	v_cmp_ne_u32_e64 s[6:7], 1, v126
	s_andn2_b64 vcc, exec, s[8:9]
	v_lshlrev_b32_e32 v126, 16, v122
	v_and_b32_e32 v122, 0xffff0000, v122
	v_lshlrev_b32_e32 v127, 16, v123
	v_and_b32_e32 v123, 0xffff0000, v123
	v_lshlrev_b32_e32 v128, 16, v124
	v_and_b32_e32 v124, 0xffff0000, v124
	v_lshlrev_b32_e32 v129, 16, v125
	v_and_b32_e32 v125, 0xffff0000, v125
	v_mul_f32_e32 v126, 0xbfb8aa3b, v126
	v_mul_f32_e32 v128, 0xbfb8aa3b, v128
	v_mul_f32_e32 v122, 0xbfb8aa3b, v122
	v_mul_f32_e32 v124, 0xbfb8aa3b, v124
	v_mul_f32_e32 v127, 0xbfb8aa3b, v127
	v_mul_f32_e32 v129, 0xbfb8aa3b, v129
	v_mul_f32_e32 v123, 0xbfb8aa3b, v123
	v_mul_f32_e32 v125, 0xbfb8aa3b, v125
	v_exp_f32_e32 v126, v126
	v_exp_f32_e32 v128, v128
	v_exp_f32_e32 v122, v122
	v_exp_f32_e32 v124, v124
	v_exp_f32_e32 v127, v127
	v_exp_f32_e32 v129, v129
	v_exp_f32_e32 v123, v123
	v_exp_f32_e32 v125, v125
	v_add_f32_e32 v126, 1.0, v126
	v_add_f32_e32 v128, 1.0, v128
	v_add_f32_e32 v143, 1.0, v122
	v_add_f32_e32 v144, 1.0, v124
	v_add_f32_e32 v127, 1.0, v127
	v_add_f32_e32 v129, 1.0, v129
	v_add_f32_e32 v145, 1.0, v123
	v_add_f32_e32 v125, 1.0, v125
	v_rcp_f32_e32 v122, v126
	v_rcp_f32_e32 v124, v128
	v_rcp_f32_e32 v123, v143
	v_rcp_f32_e32 v126, v127
	v_rcp_f32_e32 v127, v145
	v_rcp_f32_e32 v128, v129
	v_rcp_f32_e32 v129, v125
	v_rcp_f32_e32 v125, v144
	v_pk_mul_f32 v[120:121], v[120:121], v[126:127]
	v_pk_mul_f32 v[118:119], v[118:119], v[122:123]
	v_pk_mul_f32 v[116:117], v[116:117], v[128:129]
	v_pk_mul_f32 v[114:115], v[114:115], v[124:125]
	s_cbranch_vccnz .LBB0_124
	global_load_dwordx4 v[122:125], v[252:253], off
	global_load_dwordx4 v[126:129], v[252:253], off offset:1024
	s_waitcnt vmcnt(0)
	v_pk_add_f32 v[120:121], v[120:121], v[124:125]
	v_pk_add_f32 v[118:119], v[118:119], v[122:123]
	v_pk_add_f32 v[116:117], v[116:117], v[128:129]
	v_pk_add_f32 v[114:115], v[114:115], v[126:127]

; __device__ __forceinline__ float sigm(float x) { return rcpf_(1.f + __expf(-x)); }
; __device__ __forceinline__ void unpack8(u32x4 w, float* e) { e[0] = lo_bf(w.x); e[1] = hi_bf(w.x); e[2] = lo_bf(w.y); e[3] = hi_bf(w.y); e[4] = lo_bf(w.z); e[5] = hi_bf(w.z); e[6] = lo_bf(w.w); e[7] = hi_bf(w.w); }
;     __device__ __forceinline__ void operator()(const f32x4 (&acc)[2][2][4][2], const Unit& u, int wr, int wc, int fr, int fq) const {
;     ...
;                 const int row = row0 + ai * 128 + m * 16;
; #pragma unroll
;                 for (int bj = 0; bj < 2; ++bj) {
;                     const int col = colt + bj * 128;
;                     const u32x4 gw = *(const u32x4*)(P + (size_t)row * NIN + C_GM + u.z * 1024 + col);
;                     float gt[8]; unpack8(gw, gt);
;                     f32x4 v0 = acc[ai][bj][m][0], v1 = acc[ai][bj][m][1];
; #pragma unroll
;                     for (int j = 0; j < 4; ++j) { v0[j] *= sigm(gt[j]); v1[j] *= sigm(gt[4 + j]); }
;                     float* tp = tmp + (size_t)row * 1024 + col;
;                     if (u.z > 0) { v0 += *(const f32x4*)tp; v1 += *(const f32x4*)(tp + 4); }
;                     if (u.z < 2) { *(f32x4*)tp = v0; *(f32x4*)(tp + 4) = v1; }
.LBB0_126:
	s_andn2_b64 vcc, exec, s[44:45]
	s_cbranch_vccnz .LBB0_128
	global_store_dwordx4 v[252:253], v[118:121], off
	global_store_dwordx4 v[252:253], v[114:117], off offset:1024
.LBB0_128:
	s_nop 1
	v_or_b32_e32 v116, 16, v142
	v_mov_b64_e32 v[114:115], s[12:13]
	v_mad_i64_i32 v[114:115], s[44:45], v116, s43, v[114:115]
	v_lshl_add_u64 v[114:115], s[38:39], 1, v[114:115]
	v_lshl_add_u64 v[114:115], v[140:141], 1, v[114:115]
	v_add_co_u32_e32 v118, vcc, 0x4000, v114
	v_ashrrev_i32_e32 v117, 31, v116
	s_nop 0
	v_addc_co_u32_e32 v119, vcc, 0, v115, vcc
	v_lshl_add_u64 v[252:253], v[252:253], 0, s[98:99]
	v_mov_b32_e32 v118, v162
	v_mov_b32_e32 v119, v163
	v_mov_b32_e32 v120, v164
	v_mov_b32_e32 v121, v165
	s_and_b64 vcc, exec, s[6:7]
	v_lshlrev_b32_e32 v124, 16, v119
	v_and_b32_e32 v125, 0xffff0000, v119
	v_lshlrev_b32_e32 v119, 16, v120
	v_mul_f32_e32 v119, 0xbfb8aa3b, v119
	v_exp_f32_e32 v119, v119
	v_lshlrev_b32_e32 v122, 16, v118
	v_and_b32_e32 v123, 0xffff0000, v118
	v_and_b32_e32 v126, 0xffff0000, v120
	v_add_f32_e32 v119, 1.0, v119
	v_mul_f32_e32 v118, 0xbfb8aa3b, v122
	v_rcp_f32_e32 v120, v119
	v_mul_f32_e32 v119, 0xbfb8aa3b, v123
	v_exp_f32_e32 v118, v118
	v_exp_f32_e32 v119, v119
	v_lshlrev_b32_e32 v127, 16, v121
	v_mul_f32_e32 v123, 0xbfb8aa3b, v127
	v_add_f32_e32 v118, 1.0, v118
	v_add_f32_e32 v119, 1.0, v119
	v_exp_f32_e32 v123, v123
	v_rcp_f32_e32 v118, v118
	v_rcp_f32_e32 v119, v119
	v_and_b32_e32 v128, 0xffff0000, v121
	v_add_f32_e32 v123, 1.0, v123
	v_mul_f32_e32 v121, 0xbfb8aa3b, v126
	v_mul_f32_e32 v122, 0xbfb8aa3b, v124
	v_rcp_f32_e32 v124, v123
	v_mul_f32_e32 v123, 0xbfb8aa3b, v125
	v_pk_mul_f32 v[110:111], v[110:111], v[118:119]
	v_mul_f32_e32 v118, 0xbfb8aa3b, v128
	v_exp_f32_e32 v121, v121
	v_exp_f32_e32 v122, v122
	v_exp_f32_e32 v123, v123
	v_exp_f32_e32 v118, v118
	v_add_f32_e32 v121, 1.0, v121
	v_add_f32_e32 v122, 1.0, v122
	v_add_f32_e32 v123, 1.0, v123
	v_add_f32_e32 v118, 1.0, v118
	v_rcp_f32_e32 v121, v121
	v_rcp_f32_e32 v122, v122
	v_rcp_f32_e32 v123, v123
	v_rcp_f32_e32 v125, v118
	v_lshlrev_b64 v[118:119], 12, v[116:117]
	v_lshl_add_u64 v[118:119], s[16:17], 0, v[118:119]
	v_pk_mul_f32 v[112:113], v[112:113], v[122:123]
	v_pk_mul_f32 v[108:109], v[108:109], v[124:125]
	v_pk_mul_f32 v[106:107], v[106:107], v[120:121]
	v_lshl_add_u64 v[118:119], v[140:141], 2, v[118:119]
	s_cbranch_vccnz .LBB0_130
	global_load_dwordx4 v[120:123], v[252:253], off
	global_load_dwordx4 v[124:127], v[252:253], off offset:1024
	s_waitcnt vmcnt(0)
	v_pk_add_f32 v[112:113], v[112:113], v[122:123]
	v_pk_add_f32 v[110:111], v[110:111], v[120:121]
	v_pk_add_f32 v[108:109], v[108:109], v[126:127]
	v_pk_add_f32 v[106:107], v[106:107], v[124:125]

; __device__ __forceinline__ float sigm(float x) { return rcpf_(1.f + __expf(-x)); }
; __device__ __forceinline__ void unpack8(u32x4 w, float* e) { e[0] = lo_bf(w.x); e[1] = hi_bf(w.x); e[2] = lo_bf(w.y); e[3] = hi_bf(w.y); e[4] = lo_bf(w.z); e[5] = hi_bf(w.z); e[6] = lo_bf(w.w); e[7] = hi_bf(w.w); }
;     __device__ __forceinline__ void operator()(const f32x4 (&acc)[2][2][4][2], const Unit& u, int wr, int wc, int fr, int fq) const {
;     ...
;                     const int col = colt + bj * 128;
;                     const u32x4 gw = *(const u32x4*)(P + (size_t)row * NIN + C_GM + u.z * 1024 + col);
;                     float gt[8]; unpack8(gw, gt);
;                     f32x4 v0 = acc[ai][bj][m][0], v1 = acc[ai][bj][m][1];
; #pragma unroll
;                     for (int j = 0; j < 4; ++j) { v0[j] *= sigm(gt[j]); v1[j] *= sigm(gt[4 + j]); }
;                     float* tp = tmp + (size_t)row * 1024 + col;
;                     if (u.z > 0) { v0 += *(const f32x4*)tp; v1 += *(const f32x4*)(tp + 4); }
;                     if (u.z < 2) { *(f32x4*)tp = v0; *(f32x4*)(tp + 4) = v1; }
.LBB0_132:
	s_andn2_b64 vcc, exec, s[44:45]
	s_cbranch_vccnz .LBB0_134
	global_store_dwordx4 v[252:253], v[110:113], off
	global_store_dwordx4 v[252:253], v[106:109], off offset:1024
.LBB0_134:
	s_mov_b64 s[44:45], 0x4000
	s_nop 0
	v_lshl_add_u64 v[106:107], v[114:115], 0, s[44:45]
	v_lshl_add_u64 v[252:253], v[252:253], 0, s[98:99]
	v_mov_b32_e32 v106, v200
	v_mov_b32_e32 v107, v201
	v_mov_b32_e32 v108, v202
	v_mov_b32_e32 v109, v203
	s_and_b64 vcc, exec, s[6:7]
	v_lshlrev_b32_e32 v110, 16, v106
	v_and_b32_e32 v106, 0xffff0000, v106
	v_lshlrev_b32_e32 v111, 16, v107
	v_and_b32_e32 v107, 0xffff0000, v107
	v_lshlrev_b32_e32 v112, 16, v108
	v_and_b32_e32 v108, 0xffff0000, v108
	v_lshlrev_b32_e32 v113, 16, v109
	v_and_b32_e32 v109, 0xffff0000, v109
	v_mul_f32_e32 v110, 0xbfb8aa3b, v110
	v_mul_f32_e32 v112, 0xbfb8aa3b, v112
	v_mul_f32_e32 v106, 0xbfb8aa3b, v106
	v_mul_f32_e32 v108, 0xbfb8aa3b, v108
	v_mul_f32_e32 v111, 0xbfb8aa3b, v111
	v_mul_f32_e32 v113, 0xbfb8aa3b, v113
	v_mul_f32_e32 v107, 0xbfb8aa3b, v107
	v_mul_f32_e32 v109, 0xbfb8aa3b, v109
	v_exp_f32_e32 v110, v110
	v_exp_f32_e32 v112, v112
	v_exp_f32_e32 v106, v106
	v_exp_f32_e32 v108, v108
	v_exp_f32_e32 v111, v111
	v_exp_f32_e32 v113, v113
	v_exp_f32_e32 v107, v107
	v_exp_f32_e32 v109, v109
	v_add_f32_e32 v110, 1.0, v110
	v_add_f32_e32 v112, 1.0, v112
	v_add_f32_e32 v114, 1.0, v106
	v_add_f32_e32 v115, 1.0, v108
	v_add_f32_e32 v111, 1.0, v111
	v_add_f32_e32 v113, 1.0, v113
	v_add_f32_e32 v120, 1.0, v107
	v_add_f32_e32 v109, 1.0, v109
	v_rcp_f32_e32 v106, v110
	v_rcp_f32_e32 v108, v112
	v_rcp_f32_e32 v107, v114
	v_rcp_f32_e32 v110, v111
	v_rcp_f32_e32 v111, v120
	v_rcp_f32_e32 v112, v113
	v_rcp_f32_e32 v113, v109
	v_rcp_f32_e32 v109, v115
	v_pk_mul_f32 v[104:105], v[104:105], v[110:111]
	v_pk_mul_f32 v[102:103], v[102:103], v[106:107]
	v_pk_mul_f32 v[100:101], v[100:101], v[112:113]
	v_pk_mul_f32 v[98:99], v[98:99], v[108:109]
	s_cbranch_vccnz .LBB0_136
	global_load_dwordx4 v[106:109], v[252:253], off
	global_load_dwordx4 v[110:113], v[252:253], off offset:1024
	s_waitcnt vmcnt(0)
	v_pk_add_f32 v[104:105], v[104:105], v[108:109]
	v_pk_add_f32 v[102:103], v[102:103], v[106:107]
	v_pk_add_f32 v[100:101], v[100:101], v[112:113]
	v_pk_add_f32 v[98:99], v[98:99], v[110:111]

; __device__ __forceinline__ float sigm(float x) { return rcpf_(1.f + __expf(-x)); }
; __device__ __forceinline__ void unpack8(u32x4 w, float* e) { e[0] = lo_bf(w.x); e[1] = hi_bf(w.x); e[2] = lo_bf(w.y); e[3] = hi_bf(w.y); e[4] = lo_bf(w.z); e[5] = hi_bf(w.z); e[6] = lo_bf(w.w); e[7] = hi_bf(w.w); }
;     __device__ __forceinline__ void operator()(const f32x4 (&acc)[2][2][4][2], const Unit& u, int wr, int wc, int fr, int fq) const {
;     ...
;                 const int row = row0 + ai * 128 + m * 16;
; #pragma unroll
;                 for (int bj = 0; bj < 2; ++bj) {
;                     const int col = colt + bj * 128;
;                     const u32x4 gw = *(const u32x4*)(P + (size_t)row * NIN + C_GM + u.z * 1024 + col);
;                     float gt[8]; unpack8(gw, gt);
;                     f32x4 v0 = acc[ai][bj][m][0], v1 = acc[ai][bj][m][1];
; #pragma unroll
;                     for (int j = 0; j < 4; ++j) { v0[j] *= sigm(gt[j]); v1[j] *= sigm(gt[4 + j]); }
;                     float* tp = tmp + (size_t)row * 1024 + col;
;                     if (u.z > 0) { v0 += *(const f32x4*)tp; v1 += *(const f32x4*)(tp + 4); }
;                     if (u.z < 2) { *(f32x4*)tp = v0; *(f32x4*)(tp + 4) = v1; }
.LBB0_138:
	s_andn2_b64 vcc, exec, s[44:45]
	s_cbranch_vccnz .LBB0_140
	global_store_dwordx4 v[252:253], v[102:105], off
	global_store_dwordx4 v[252:253], v[98:101], off offset:1024
.LBB0_140:
	s_nop 1
	v_or_b32_e32 v100, 32, v142
	v_mov_b64_e32 v[98:99], s[12:13]
	v_mad_i64_i32 v[98:99], s[44:45], v100, s43, v[98:99]
	v_lshl_add_u64 v[98:99], s[38:39], 1, v[98:99]
	v_lshl_add_u64 v[98:99], v[140:141], 1, v[98:99]
	v_add_co_u32_e32 v102, vcc, 0x4000, v98
	v_ashrrev_i32_e32 v101, 31, v100
	s_nop 0
	v_addc_co_u32_e32 v103, vcc, 0, v99, vcc
	v_lshl_add_u64 v[252:253], v[252:253], 0, s[98:99]
	v_mov_b32_e32 v102, v166
	v_mov_b32_e32 v103, v167
	v_mov_b32_e32 v104, v168
	v_mov_b32_e32 v105, v169
	s_and_b64 vcc, exec, s[6:7]
	v_lshlrev_b32_e32 v108, 16, v103
	v_and_b32_e32 v109, 0xffff0000, v103
	v_lshlrev_b32_e32 v103, 16, v104
	v_mul_f32_e32 v103, 0xbfb8aa3b, v103
	v_exp_f32_e32 v103, v103
	v_lshlrev_b32_e32 v106, 16, v102
	v_and_b32_e32 v107, 0xffff0000, v102
	v_and_b32_e32 v110, 0xffff0000, v104
	v_add_f32_e32 v103, 1.0, v103
	v_mul_f32_e32 v102, 0xbfb8aa3b, v106
	v_rcp_f32_e32 v104, v103
	v_mul_f32_e32 v103, 0xbfb8aa3b, v107
	v_exp_f32_e32 v102, v102
	v_exp_f32_e32 v103, v103
	v_lshlrev_b32_e32 v111, 16, v105
	v_mul_f32_e32 v107, 0xbfb8aa3b, v111
	v_add_f32_e32 v102, 1.0, v102
	v_add_f32_e32 v103, 1.0, v103
	v_exp_f32_e32 v107, v107
	v_rcp_f32_e32 v102, v102
	v_rcp_f32_e32 v103, v103
	v_and_b32_e32 v112, 0xffff0000, v105
	v_add_f32_e32 v107, 1.0, v107
	v_mul_f32_e32 v105, 0xbfb8aa3b, v110
	v_mul_f32_e32 v106, 0xbfb8aa3b, v108
	v_rcp_f32_e32 v108, v107
	v_mul_f32_e32 v107, 0xbfb8aa3b, v109
	v_pk_mul_f32 v[94:95], v[94:95], v[102:103]
	v_mul_f32_e32 v102, 0xbfb8aa3b, v112
	v_exp_f32_e32 v105, v105
	v_exp_f32_e32 v106, v106
	v_exp_f32_e32 v107, v107
	v_exp_f32_e32 v102, v102
	v_add_f32_e32 v105, 1.0, v105
	v_add_f32_e32 v106, 1.0, v106
	v_add_f32_e32 v107, 1.0, v107
	v_add_f32_e32 v102, 1.0, v102
	v_rcp_f32_e32 v105, v105
	v_rcp_f32_e32 v106, v106
	v_rcp_f32_e32 v107, v107
	v_rcp_f32_e32 v109, v102
	v_lshlrev_b64 v[102:103], 12, v[100:101]
	v_lshl_add_u64 v[102:103], s[16:17], 0, v[102:103]
	v_pk_mul_f32 v[96:97], v[96:97], v[106:107]
	v_pk_mul_f32 v[92:93], v[92:93], v[108:109]
	v_pk_mul_f32 v[90:91], v[90:91], v[104:105]
	v_lshl_add_u64 v[102:103], v[140:141], 2, v[102:103]
	s_cbranch_vccnz .LBB0_142
	global_load_dwordx4 v[104:107], v[252:253], off
	global_load_dwordx4 v[108:111], v[252:253], off offset:1024
	s_waitcnt vmcnt(0)
	v_pk_add_f32 v[96:97], v[96:97], v[106:107]
	v_pk_add_f32 v[94:95], v[94:95], v[104:105]
	v_pk_add_f32 v[92:93], v[92:93], v[110:111]
	v_pk_add_f32 v[90:91], v[90:91], v[108:109]

; __device__ __forceinline__ unsigned cvt_pk_bf16(float lo, float hi) { unsigned r; asm("v_cvt_pk_bf16_f32 %0, %1, %2" : "=v"(r) : "v"(lo), "v"(hi)); return r; }
; __device__ __forceinline__ float sigm(float x) { return rcpf_(1.f + __expf(-x)); }
; __device__ __forceinline__ void unpack8(u32x4 w, float* e) { e[0] = lo_bf(w.x); e[1] = hi_bf(w.x); e[2] = lo_bf(w.y); e[3] = hi_bf(w.y); e[4] = lo_bf(w.z); e[5] = hi_bf(w.z); e[6] = lo_bf(w.w); e[7] = hi_bf(w.w); }
;     __device__ __forceinline__ void operator()(const f32x4 (&acc)[2][2][4][2], const Unit& u, int wr, int wc, int fr, int fq) const {
;     ...
;                     const int col = colt + bj * 128;
;                     const u32x4 gw = *(const u32x4*)(P + (size_t)row * NIN + C_GM + u.z * 1024 + col);
;                     float gt[8]; unpack8(gw, gt);
;                     f32x4 v0 = acc[ai][bj][m][0], v1 = acc[ai][bj][m][1];
; #pragma unroll
;                     for (int j = 0; j < 4; ++j) { v0[j] *= sigm(gt[j]); v1[j] *= sigm(gt[4 + j]); }
;                     float* tp = tmp + (size_t)row * 1024 + col;
;                     if (u.z > 0) { v0 += *(const f32x4*)tp; v1 += *(const f32x4*)(tp + 4); }
;                     if (u.z < 2) { *(f32x4*)tp = v0; *(f32x4*)(tp + 4) = v1; }
;                     else { u32x4 w; w.x = cvt_pk_bf16(v0[0], v0[1]); w.y = cvt_pk_bf16(v0[2], v0[3]); w.z = cvt_pk_bf16(v1[0], v1[1]); w.w = cvt_pk_bf16(v1[2], v1[3]);
;                         *(u32x4*)(merged + (size_t)row * 1024 + col) = w; }
.LBB0_144:
	s_andn2_b64 vcc, exec, s[44:45]
	s_cbranch_vccnz .LBB0_146
	global_store_dwordx4 v[252:253], v[94:97], off
	global_store_dwordx4 v[252:253], v[90:93], off offset:1024
.LBB0_146:
	s_mov_b64 s[44:45], 0x4000
	s_nop 0
	v_lshl_add_u64 v[90:91], v[98:99], 0, s[44:45]
	v_lshl_add_u64 v[252:253], v[252:253], 0, s[98:99]
	v_mov_b32_e32 v90, v204
	v_mov_b32_e32 v91, v205
	v_mov_b32_e32 v92, v206
	v_mov_b32_e32 v93, v207
	s_and_b64 vcc, exec, s[6:7]
	v_lshlrev_b32_e32 v94, 16, v90
	v_and_b32_e32 v90, 0xffff0000, v90
	v_lshlrev_b32_e32 v95, 16, v91
	v_and_b32_e32 v91, 0xffff0000, v91
	v_lshlrev_b32_e32 v96, 16, v92
	v_and_b32_e32 v92, 0xffff0000, v92
	v_lshlrev_b32_e32 v97, 16, v93
	v_and_b32_e32 v93, 0xffff0000, v93
	v_mul_f32_e32 v94, 0xbfb8aa3b, v94
	v_mul_f32_e32 v96, 0xbfb8aa3b, v96
	v_mul_f32_e32 v90, 0xbfb8aa3b, v90
	v_mul_f32_e32 v92, 0xbfb8aa3b, v92
	v_mul_f32_e32 v95, 0xbfb8aa3b, v95
	v_mul_f32_e32 v97, 0xbfb8aa3b, v97
	v_mul_f32_e32 v91, 0xbfb8aa3b, v91
	v_mul_f32_e32 v93, 0xbfb8aa3b, v93
	v_exp_f32_e32 v94, v94
	v_exp_f32_e32 v96, v96
	v_exp_f32_e32 v90, v90
	v_exp_f32_e32 v92, v92
	v_exp_f32_e32 v95, v95
	v_exp_f32_e32 v97, v97
	v_exp_f32_e32 v91, v91
	v_exp_f32_e32 v93, v93
	v_add_f32_e32 v94, 1.0, v94
	v_add_f32_e32 v96, 1.0, v96
	v_add_f32_e32 v98, 1.0, v90
	v_add_f32_e32 v99, 1.0, v92
	v_add_f32_e32 v95, 1.0, v95
	v_add_f32_e32 v97, 1.0, v97
	v_add_f32_e32 v104, 1.0, v91
	v_add_f32_e32 v93, 1.0, v93
	v_rcp_f32_e32 v90, v94
	v_rcp_f32_e32 v92, v96
	v_rcp_f32_e32 v91, v98
	v_rcp_f32_e32 v94, v95
	v_rcp_f32_e32 v95, v104
	v_rcp_f32_e32 v96, v97
	v_rcp_f32_e32 v97, v93
	v_rcp_f32_e32 v93, v99
	v_pk_mul_f32 v[88:89], v[88:89], v[94:95]
	v_pk_mul_f32 v[86:87], v[86:87], v[90:91]
	v_pk_mul_f32 v[84:85], v[84:85], v[96:97]
	v_pk_mul_f32 v[82:83], v[82:83], v[92:93]
	s_cbranch_vccnz .LBB0_148
	global_load_dwordx4 v[90:93], v[252:253], off
	global_load_dwordx4 v[94:97], v[252:253], off offset:1024
	s_waitcnt vmcnt(0)
	v_pk_add_f32 v[88:89], v[88:89], v[92:93]
	v_pk_add_f32 v[86:87], v[86:87], v[90:91]
	v_pk_add_f32 v[84:85], v[84:85], v[96:97]
	v_pk_add_f32 v[82:83], v[82:83], v[94:95]

; __device__ __forceinline__ unsigned cvt_pk_bf16(float lo, float hi) { unsigned r; asm("v_cvt_pk_bf16_f32 %0, %1, %2" : "=v"(r) : "v"(lo), "v"(hi)); return r; }
; __device__ __forceinline__ float sigm(float x) { return rcpf_(1.f + __expf(-x)); }
; __device__ __forceinline__ void unpack8(u32x4 w, float* e) { e[0] = lo_bf(w.x); e[1] = hi_bf(w.x); e[2] = lo_bf(w.y); e[3] = hi_bf(w.y); e[4] = lo_bf(w.z); e[5] = hi_bf(w.z); e[6] = lo_bf(w.w); e[7] = hi_bf(w.w); }
;     __device__ __forceinline__ void operator()(const f32x4 (&acc)[2][2][4][2], const Unit& u, int wr, int wc, int fr, int fq) const {
;     ...
;                 const int row = row0 + ai * 128 + m * 16;
;     ...
;                     const int col = colt + bj * 128;
;                     const u32x4 gw = *(const u32x4*)(P + (size_t)row * NIN + C_GM + u.z * 1024 + col);
;                     float gt[8]; unpack8(gw, gt);
;                     f32x4 v0 = acc[ai][bj][m][0], v1 = acc[ai][bj][m][1];
; #pragma unroll
;                     for (int j = 0; j < 4; ++j) { v0[j] *= sigm(gt[j]); v1[j] *= sigm(gt[4 + j]); }
;                     float* tp = tmp + (size_t)row * 1024 + col;
;                     if (u.z > 0) { v0 += *(const f32x4*)tp; v1 += *(const f32x4*)(tp + 4); }
;                     if (u.z < 2) { *(f32x4*)tp = v0; *(f32x4*)(tp + 4) = v1; }
;                     else { u32x4 w; w.x = cvt_pk_bf16(v0[0], v0[1]); w.y = cvt_pk_bf16(v0[2], v0[3]); w.z = cvt_pk_bf16(v1[0], v1[1]); w.w = cvt_pk_bf16(v1[2], v1[3]);
;                         *(u32x4*)(merged + (size_t)row * 1024 + col) = w; }
.LBB0_150:
	s_andn2_b64 vcc, exec, s[44:45]
	s_cbranch_vccnz .LBB0_152
	global_store_dwordx4 v[252:253], v[86:89], off
	global_store_dwordx4 v[252:253], v[82:85], off offset:1024
.LBB0_152:
	s_nop 1
	v_or_b32_e32 v84, 48, v142
	v_mov_b64_e32 v[82:83], s[12:13]
	v_mad_i64_i32 v[82:83], s[44:45], v84, s43, v[82:83]
	v_lshl_add_u64 v[82:83], s[38:39], 1, v[82:83]
	v_lshl_add_u64 v[82:83], v[140:141], 1, v[82:83]
	v_add_co_u32_e32 v86, vcc, 0x4000, v82
	v_ashrrev_i32_e32 v85, 31, v84
	s_nop 0
	v_addc_co_u32_e32 v87, vcc, 0, v83, vcc
	v_lshl_add_u64 v[252:253], v[252:253], 0, s[98:99]
	v_mov_b32_e32 v86, v170
	v_mov_b32_e32 v87, v171
	v_mov_b32_e32 v88, v172
	v_mov_b32_e32 v89, v173
	s_and_b64 vcc, exec, s[6:7]
	v_lshlrev_b32_e32 v92, 16, v87
	v_and_b32_e32 v93, 0xffff0000, v87
	v_lshlrev_b32_e32 v87, 16, v88
	v_mul_f32_e32 v87, 0xbfb8aa3b, v87
	v_exp_f32_e32 v87, v87
	v_lshlrev_b32_e32 v90, 16, v86
	v_and_b32_e32 v91, 0xffff0000, v86
	v_and_b32_e32 v94, 0xffff0000, v88
	v_add_f32_e32 v87, 1.0, v87
	v_mul_f32_e32 v86, 0xbfb8aa3b, v90
	v_rcp_f32_e32 v88, v87
	v_mul_f32_e32 v87, 0xbfb8aa3b, v91
	v_exp_f32_e32 v86, v86
	v_exp_f32_e32 v87, v87
	v_lshlrev_b32_e32 v95, 16, v89
	v_mul_f32_e32 v91, 0xbfb8aa3b, v95
	v_add_f32_e32 v86, 1.0, v86
	v_add_f32_e32 v87, 1.0, v87
	v_exp_f32_e32 v91, v91
	v_rcp_f32_e32 v86, v86
	v_rcp_f32_e32 v87, v87
	v_and_b32_e32 v96, 0xffff0000, v89
	v_add_f32_e32 v91, 1.0, v91
	v_mul_f32_e32 v89, 0xbfb8aa3b, v94
	v_mul_f32_e32 v90, 0xbfb8aa3b, v92
	v_rcp_f32_e32 v92, v91
	v_mul_f32_e32 v91, 0xbfb8aa3b, v93
	v_pk_mul_f32 v[78:79], v[78:79], v[86:87]
	v_mul_f32_e32 v86, 0xbfb8aa3b, v96
	v_exp_f32_e32 v89, v89
	v_exp_f32_e32 v90, v90
	v_exp_f32_e32 v91, v91
	v_exp_f32_e32 v86, v86
	v_add_f32_e32 v89, 1.0, v89
	v_add_f32_e32 v90, 1.0, v90
	v_add_f32_e32 v91, 1.0, v91
	v_add_f32_e32 v86, 1.0, v86
	v_rcp_f32_e32 v89, v89
	v_rcp_f32_e32 v90, v90
	v_rcp_f32_e32 v91, v91
	v_rcp_f32_e32 v93, v86
	v_lshlrev_b64 v[86:87], 12, v[84:85]
	v_lshl_add_u64 v[86:87], s[16:17], 0, v[86:87]
	v_pk_mul_f32 v[80:81], v[80:81], v[90:91]
	v_pk_mul_f32 v[76:77], v[76:77], v[92:93]
	v_pk_mul_f32 v[74:75], v[74:75], v[88:89]
	v_lshl_add_u64 v[86:87], v[140:141], 2, v[86:87]
	s_cbranch_vccnz .LBB0_154
	global_load_dwordx4 v[88:91], v[252:253], off
	global_load_dwordx4 v[92:95], v[252:253], off offset:1024
	s_waitcnt vmcnt(0)
	v_pk_add_f32 v[80:81], v[80:81], v[90:91]
	v_pk_add_f32 v[78:79], v[78:79], v[88:89]
	v_pk_add_f32 v[76:77], v[76:77], v[94:95]
	v_pk_add_f32 v[74:75], v[74:75], v[92:93]

; __device__ __forceinline__ unsigned cvt_pk_bf16(float lo, float hi) { unsigned r; asm("v_cvt_pk_bf16_f32 %0, %1, %2" : "=v"(r) : "v"(lo), "v"(hi)); return r; }
; __device__ __forceinline__ float sigm(float x) { return rcpf_(1.f + __expf(-x)); }
; __device__ __forceinline__ void unpack8(u32x4 w, float* e) { e[0] = lo_bf(w.x); e[1] = hi_bf(w.x); e[2] = lo_bf(w.y); e[3] = hi_bf(w.y); e[4] = lo_bf(w.z); e[5] = hi_bf(w.z); e[6] = lo_bf(w.w); e[7] = hi_bf(w.w); }
;     __device__ __forceinline__ void operator()(const f32x4 (&acc)[2][2][4][2], const Unit& u, int wr, int wc, int fr, int fq) const {
;     ...
;                     const int col = colt + bj * 128;
;                     const u32x4 gw = *(const u32x4*)(P + (size_t)row * NIN + C_GM + u.z * 1024 + col);
;                     float gt[8]; unpack8(gw, gt);
;                     f32x4 v0 = acc[ai][bj][m][0], v1 = acc[ai][bj][m][1];
; #pragma unroll
;                     for (int j = 0; j < 4; ++j) { v0[j] *= sigm(gt[j]); v1[j] *= sigm(gt[4 + j]); }
;                     float* tp = tmp + (size_t)row * 1024 + col;
;                     if (u.z > 0) { v0 += *(const f32x4*)tp; v1 += *(const f32x4*)(tp + 4); }
;                     if (u.z < 2) { *(f32x4*)tp = v0; *(f32x4*)(tp + 4) = v1; }
;                     else { u32x4 w; w.x = cvt_pk_bf16(v0[0], v0[1]); w.y = cvt_pk_bf16(v0[2], v0[3]); w.z = cvt_pk_bf16(v1[0], v1[1]); w.w = cvt_pk_bf16(v1[2], v1[3]);
;                         *(u32x4*)(merged + (size_t)row * 1024 + col) = w; }
.LBB0_156:
	s_andn2_b64 vcc, exec, s[44:45]
	s_cbranch_vccnz .LBB0_158
	global_store_dwordx4 v[252:253], v[78:81], off
	global_store_dwordx4 v[252:253], v[74:77], off offset:1024
.LBB0_158:
	s_mov_b64 s[44:45], 0x4000
	s_nop 0
	v_lshl_add_u64 v[74:75], v[82:83], 0, s[44:45]
	v_lshl_add_u64 v[252:253], v[252:253], 0, s[98:99]
	v_mov_b32_e32 v74, v208
	v_mov_b32_e32 v75, v209
	v_mov_b32_e32 v76, v210
	v_mov_b32_e32 v77, v211
	s_and_b64 vcc, exec, s[6:7]
	v_lshlrev_b32_e32 v78, 16, v74
	v_and_b32_e32 v74, 0xffff0000, v74
	v_lshlrev_b32_e32 v79, 16, v75
	v_and_b32_e32 v75, 0xffff0000, v75
	v_lshlrev_b32_e32 v80, 16, v76
	v_and_b32_e32 v76, 0xffff0000, v76
	v_lshlrev_b32_e32 v81, 16, v77
	v_and_b32_e32 v77, 0xffff0000, v77
	v_mul_f32_e32 v78, 0xbfb8aa3b, v78
	v_mul_f32_e32 v80, 0xbfb8aa3b, v80
	v_mul_f32_e32 v74, 0xbfb8aa3b, v74
	v_mul_f32_e32 v76, 0xbfb8aa3b, v76
	v_mul_f32_e32 v79, 0xbfb8aa3b, v79
	v_mul_f32_e32 v81, 0xbfb8aa3b, v81
	v_mul_f32_e32 v75, 0xbfb8aa3b, v75
	v_mul_f32_e32 v77, 0xbfb8aa3b, v77
	v_exp_f32_e32 v78, v78
	v_exp_f32_e32 v80, v80
	v_exp_f32_e32 v74, v74
	v_exp_f32_e32 v76, v76
	v_exp_f32_e32 v79, v79
	v_exp_f32_e32 v81, v81
	v_exp_f32_e32 v75, v75
	v_exp_f32_e32 v77, v77
	v_add_f32_e32 v78, 1.0, v78
	v_add_f32_e32 v80, 1.0, v80
	v_add_f32_e32 v82, 1.0, v74
	v_add_f32_e32 v83, 1.0, v76
	v_add_f32_e32 v79, 1.0, v79
	v_add_f32_e32 v81, 1.0, v81
	v_add_f32_e32 v88, 1.0, v75
	v_add_f32_e32 v77, 1.0, v77
	v_rcp_f32_e32 v74, v78
	v_rcp_f32_e32 v76, v80
	v_rcp_f32_e32 v75, v82
	v_rcp_f32_e32 v78, v79
	v_rcp_f32_e32 v79, v88
	v_rcp_f32_e32 v80, v81
	v_rcp_f32_e32 v81, v77
	v_rcp_f32_e32 v77, v83
	v_pk_mul_f32 v[72:73], v[72:73], v[78:79]
	v_pk_mul_f32 v[70:71], v[70:71], v[74:75]
	v_pk_mul_f32 v[68:69], v[68:69], v[80:81]
	v_pk_mul_f32 v[66:67], v[66:67], v[76:77]
	s_cbranch_vccnz .LBB0_160
	global_load_dwordx4 v[74:77], v[252:253], off
	global_load_dwordx4 v[78:81], v[252:253], off offset:1024
	s_waitcnt vmcnt(0)
	v_pk_add_f32 v[72:73], v[72:73], v[76:77]
	v_pk_add_f32 v[70:71], v[70:71], v[74:75]
	v_pk_add_f32 v[68:69], v[68:69], v[80:81]
	v_pk_add_f32 v[66:67], v[66:67], v[78:79]

; __device__ __forceinline__ unsigned cvt_pk_bf16(float lo, float hi) { unsigned r; asm("v_cvt_pk_bf16_f32 %0, %1, %2" : "=v"(r) : "v"(lo), "v"(hi)); return r; }
; __device__ __forceinline__ float sigm(float x) { return rcpf_(1.f + __expf(-x)); }
; __device__ __forceinline__ void unpack8(u32x4 w, float* e) { e[0] = lo_bf(w.x); e[1] = hi_bf(w.x); e[2] = lo_bf(w.y); e[3] = hi_bf(w.y); e[4] = lo_bf(w.z); e[5] = hi_bf(w.z); e[6] = lo_bf(w.w); e[7] = hi_bf(w.w); }
;     __device__ __forceinline__ void operator()(const f32x4 (&acc)[2][2][4][2], const Unit& u, int wr, int wc, int fr, int fq) const {
;     ...
;                 const int row = row0 + ai * 128 + m * 16;
;     ...
;                     const int col = colt + bj * 128;
;                     const u32x4 gw = *(const u32x4*)(P + (size_t)row * NIN + C_GM + u.z * 1024 + col);
;                     float gt[8]; unpack8(gw, gt);
;                     f32x4 v0 = acc[ai][bj][m][0], v1 = acc[ai][bj][m][1];
; #pragma unroll
;                     for (int j = 0; j < 4; ++j) { v0[j] *= sigm(gt[j]); v1[j] *= sigm(gt[4 + j]); }
;                     float* tp = tmp + (size_t)row * 1024 + col;
;                     if (u.z > 0) { v0 += *(const f32x4*)tp; v1 += *(const f32x4*)(tp + 4); }
;                     if (u.z < 2) { *(f32x4*)tp = v0; *(f32x4*)(tp + 4) = v1; }
;                     else { u32x4 w; w.x = cvt_pk_bf16(v0[0], v0[1]); w.y = cvt_pk_bf16(v0[2], v0[3]); w.z = cvt_pk_bf16(v1[0], v1[1]); w.w = cvt_pk_bf16(v1[2], v1[3]);
;                         *(u32x4*)(merged + (size_t)row * 1024 + col) = w; }
.LBB0_162:
	s_andn2_b64 vcc, exec, s[44:45]
	s_cbranch_vccnz .LBB0_164
	global_store_dwordx4 v[252:253], v[70:73], off
	global_store_dwordx4 v[252:253], v[66:69], off offset:1024
.LBB0_164:
	s_nop 1
	v_add_u32_e32 v68, 0x80, v142
	v_mov_b64_e32 v[66:67], s[12:13]
	v_mad_i64_i32 v[66:67], s[44:45], v68, s43, v[66:67]
	v_lshl_add_u64 v[66:67], s[38:39], 1, v[66:67]
	v_lshl_add_u64 v[66:67], v[140:141], 1, v[66:67]
	v_add_co_u32_e32 v70, vcc, 0x4000, v66
	v_ashrrev_i32_e32 v69, 31, v68
	s_nop 0
	v_addc_co_u32_e32 v71, vcc, 0, v67, vcc
	v_lshl_add_u64 v[252:253], v[252:253], 0, s[98:99]
	v_mov_b32_e32 v70, v174
	v_mov_b32_e32 v71, v175
	v_mov_b32_e32 v72, v176
	v_mov_b32_e32 v73, v177
	s_and_b64 vcc, exec, s[6:7]
	v_lshlrev_b32_e32 v76, 16, v71
	v_and_b32_e32 v77, 0xffff0000, v71
	v_lshlrev_b32_e32 v71, 16, v72
	v_mul_f32_e32 v71, 0xbfb8aa3b, v71
	v_exp_f32_e32 v71, v71
	v_lshlrev_b32_e32 v74, 16, v70
	v_and_b32_e32 v75, 0xffff0000, v70
	v_and_b32_e32 v78, 0xffff0000, v72
	v_add_f32_e32 v71, 1.0, v71
	v_mul_f32_e32 v70, 0xbfb8aa3b, v74
	v_rcp_f32_e32 v72, v71
	v_mul_f32_e32 v71, 0xbfb8aa3b, v75
	v_exp_f32_e32 v70, v70
	v_exp_f32_e32 v71, v71
	v_lshlrev_b32_e32 v79, 16, v73
	v_mul_f32_e32 v75, 0xbfb8aa3b, v79
	v_add_f32_e32 v70, 1.0, v70
	v_add_f32_e32 v71, 1.0, v71
	v_exp_f32_e32 v75, v75
	v_rcp_f32_e32 v70, v70
	v_rcp_f32_e32 v71, v71
	v_and_b32_e32 v80, 0xffff0000, v73
	v_add_f32_e32 v75, 1.0, v75
	v_mul_f32_e32 v73, 0xbfb8aa3b, v78
	v_mul_f32_e32 v74, 0xbfb8aa3b, v76
	v_rcp_f32_e32 v76, v75
	v_mul_f32_e32 v75, 0xbfb8aa3b, v77
	v_pk_mul_f32 v[62:63], v[62:63], v[70:71]
	v_mul_f32_e32 v70, 0xbfb8aa3b, v80
	v_exp_f32_e32 v73, v73
	v_exp_f32_e32 v74, v74
	v_exp_f32_e32 v75, v75
	v_exp_f32_e32 v70, v70
	v_add_f32_e32 v73, 1.0, v73
	v_add_f32_e32 v74, 1.0, v74
	v_add_f32_e32 v75, 1.0, v75
	v_add_f32_e32 v70, 1.0, v70
	v_rcp_f32_e32 v73, v73
	v_rcp_f32_e32 v74, v74
	v_rcp_f32_e32 v75, v75
	v_rcp_f32_e32 v77, v70
	v_lshlrev_b64 v[70:71], 12, v[68:69]
	v_lshl_add_u64 v[70:71], s[16:17], 0, v[70:71]
	v_pk_mul_f32 v[64:65], v[64:65], v[74:75]
	v_pk_mul_f32 v[60:61], v[60:61], v[76:77]
	v_pk_mul_f32 v[58:59], v[58:59], v[72:73]
	v_lshl_add_u64 v[70:71], v[140:141], 2, v[70:71]
	s_cbranch_vccnz .LBB0_166
	global_load_dwordx4 v[72:75], v[252:253], off
	global_load_dwordx4 v[76:79], v[252:253], off offset:1024
	s_waitcnt vmcnt(0)
	v_pk_add_f32 v[64:65], v[64:65], v[74:75]
	v_pk_add_f32 v[62:63], v[62:63], v[72:73]
	v_pk_add_f32 v[60:61], v[60:61], v[78:79]
	v_pk_add_f32 v[58:59], v[58:59], v[76:77]

; __device__ __forceinline__ unsigned cvt_pk_bf16(float lo, float hi) { unsigned r; asm("v_cvt_pk_bf16_f32 %0, %1, %2" : "=v"(r) : "v"(lo), "v"(hi)); return r; }
; __device__ __forceinline__ float sigm(float x) { return rcpf_(1.f + __expf(-x)); }
; __device__ __forceinline__ void unpack8(u32x4 w, float* e) { e[0] = lo_bf(w.x); e[1] = hi_bf(w.x); e[2] = lo_bf(w.y); e[3] = hi_bf(w.y); e[4] = lo_bf(w.z); e[5] = hi_bf(w.z); e[6] = lo_bf(w.w); e[7] = hi_bf(w.w); }
;     __device__ __forceinline__ void operator()(const f32x4 (&acc)[2][2][4][2], const Unit& u, int wr, int wc, int fr, int fq) const {
;     ...
;                     const int col = colt + bj * 128;
;                     const u32x4 gw = *(const u32x4*)(P + (size_t)row * NIN + C_GM + u.z * 1024 + col);
;                     float gt[8]; unpack8(gw, gt);
;                     f32x4 v0 = acc[ai][bj][m][0], v1 = acc[ai][bj][m][1];
; #pragma unroll
;                     for (int j = 0; j < 4; ++j) { v0[j] *= sigm(gt[j]); v1[j] *= sigm(gt[4 + j]); }
;                     float* tp = tmp + (size_t)row * 1024 + col;
;                     if (u.z > 0) { v0 += *(const f32x4*)tp; v1 += *(const f32x4*)(tp + 4); }
;                     if (u.z < 2) { *(f32x4*)tp = v0; *(f32x4*)(tp + 4) = v1; }
;                     else { u32x4 w; w.x = cvt_pk_bf16(v0[0], v0[1]); w.y = cvt_pk_bf16(v0[2], v0[3]); w.z = cvt_pk_bf16(v1[0], v1[1]); w.w = cvt_pk_bf16(v1[2], v1[3]);
;                         *(u32x4*)(merged + (size_t)row * 1024 + col) = w; }
.LBB0_168:
	s_andn2_b64 vcc, exec, s[44:45]
	s_cbranch_vccnz .LBB0_170
	global_store_dwordx4 v[252:253], v[62:65], off
	global_store_dwordx4 v[252:253], v[58:61], off offset:1024
.LBB0_170:
	s_mov_b64 s[44:45], 0x4000
	s_nop 0
	v_lshl_add_u64 v[58:59], v[66:67], 0, s[44:45]
	v_lshl_add_u64 v[252:253], v[252:253], 0, s[98:99]
	v_mov_b32_e32 v58, v212
	v_mov_b32_e32 v59, v213
	v_mov_b32_e32 v60, v214
	v_mov_b32_e32 v61, v215
	s_and_b64 vcc, exec, s[6:7]
	v_lshlrev_b32_e32 v62, 16, v58
	v_and_b32_e32 v58, 0xffff0000, v58
	v_lshlrev_b32_e32 v63, 16, v59
	v_and_b32_e32 v59, 0xffff0000, v59
	v_lshlrev_b32_e32 v64, 16, v60
	v_and_b32_e32 v60, 0xffff0000, v60
	v_lshlrev_b32_e32 v65, 16, v61
	v_and_b32_e32 v61, 0xffff0000, v61
	v_mul_f32_e32 v62, 0xbfb8aa3b, v62
	v_mul_f32_e32 v64, 0xbfb8aa3b, v64
	v_mul_f32_e32 v58, 0xbfb8aa3b, v58
	v_mul_f32_e32 v60, 0xbfb8aa3b, v60
	v_mul_f32_e32 v63, 0xbfb8aa3b, v63
	v_mul_f32_e32 v65, 0xbfb8aa3b, v65
	v_mul_f32_e32 v59, 0xbfb8aa3b, v59
	v_mul_f32_e32 v61, 0xbfb8aa3b, v61
	v_exp_f32_e32 v62, v62
	v_exp_f32_e32 v64, v64
	v_exp_f32_e32 v58, v58
	v_exp_f32_e32 v60, v60
	v_exp_f32_e32 v63, v63
	v_exp_f32_e32 v65, v65
	v_exp_f32_e32 v59, v59
	v_exp_f32_e32 v61, v61
	v_add_f32_e32 v62, 1.0, v62
	v_add_f32_e32 v64, 1.0, v64
	v_add_f32_e32 v66, 1.0, v58
	v_add_f32_e32 v67, 1.0, v60
	v_add_f32_e32 v63, 1.0, v63
	v_add_f32_e32 v65, 1.0, v65
	v_add_f32_e32 v72, 1.0, v59
	v_add_f32_e32 v61, 1.0, v61
	v_rcp_f32_e32 v58, v62
	v_rcp_f32_e32 v60, v64
	v_rcp_f32_e32 v59, v66
	v_rcp_f32_e32 v62, v63
	v_rcp_f32_e32 v63, v72
	v_rcp_f32_e32 v64, v65
	v_rcp_f32_e32 v65, v61
	v_rcp_f32_e32 v61, v67
	v_pk_mul_f32 v[56:57], v[56:57], v[62:63]
	v_pk_mul_f32 v[54:55], v[54:55], v[58:59]
	v_pk_mul_f32 v[52:53], v[52:53], v[64:65]
	v_pk_mul_f32 v[50:51], v[50:51], v[60:61]
	s_cbranch_vccnz .LBB0_172
	global_load_dwordx4 v[58:61], v[252:253], off
	global_load_dwordx4 v[62:65], v[252:253], off offset:1024
	s_waitcnt vmcnt(0)
	v_pk_add_f32 v[56:57], v[56:57], v[60:61]
	v_pk_add_f32 v[54:55], v[54:55], v[58:59]
	v_pk_add_f32 v[52:53], v[52:53], v[64:65]
	v_pk_add_f32 v[50:51], v[50:51], v[62:63]

; __device__ __forceinline__ unsigned cvt_pk_bf16(float lo, float hi) { unsigned r; asm("v_cvt_pk_bf16_f32 %0, %1, %2" : "=v"(r) : "v"(lo), "v"(hi)); return r; }
; __device__ __forceinline__ float sigm(float x) { return rcpf_(1.f + __expf(-x)); }
; __device__ __forceinline__ void unpack8(u32x4 w, float* e) { e[0] = lo_bf(w.x); e[1] = hi_bf(w.x); e[2] = lo_bf(w.y); e[3] = hi_bf(w.y); e[4] = lo_bf(w.z); e[5] = hi_bf(w.z); e[6] = lo_bf(w.w); e[7] = hi_bf(w.w); }
;     __device__ __forceinline__ void operator()(const f32x4 (&acc)[2][2][4][2], const Unit& u, int wr, int wc, int fr, int fq) const {
;     ...
;                 const int row = row0 + ai * 128 + m * 16;
;     ...
;                     const int col = colt + bj * 128;
;                     const u32x4 gw = *(const u32x4*)(P + (size_t)row * NIN + C_GM + u.z * 1024 + col);
;                     float gt[8]; unpack8(gw, gt);
;                     f32x4 v0 = acc[ai][bj][m][0], v1 = acc[ai][bj][m][1];
; #pragma unroll
;                     for (int j = 0; j < 4; ++j) { v0[j] *= sigm(gt[j]); v1[j] *= sigm(gt[4 + j]); }
;                     float* tp = tmp + (size_t)row * 1024 + col;
;                     if (u.z > 0) { v0 += *(const f32x4*)tp; v1 += *(const f32x4*)(tp + 4); }
;                     if (u.z < 2) { *(f32x4*)tp = v0; *(f32x4*)(tp + 4) = v1; }
;                     else { u32x4 w; w.x = cvt_pk_bf16(v0[0], v0[1]); w.y = cvt_pk_bf16(v0[2], v0[3]); w.z = cvt_pk_bf16(v1[0], v1[1]); w.w = cvt_pk_bf16(v1[2], v1[3]);
;                         *(u32x4*)(merged + (size_t)row * 1024 + col) = w; }
.LBB0_174:
	s_andn2_b64 vcc, exec, s[44:45]
	s_cbranch_vccnz .LBB0_176
	global_store_dwordx4 v[252:253], v[54:57], off
	global_store_dwordx4 v[252:253], v[50:53], off offset:1024
.LBB0_176:
	s_nop 1
	v_add_u32_e32 v52, 0x90, v142
	v_mov_b64_e32 v[50:51], s[12:13]
	v_mad_i64_i32 v[50:51], s[44:45], v52, s43, v[50:51]
	v_lshl_add_u64 v[50:51], s[38:39], 1, v[50:51]
	v_lshl_add_u64 v[50:51], v[140:141], 1, v[50:51]
	v_add_co_u32_e32 v54, vcc, 0x4000, v50
	v_ashrrev_i32_e32 v53, 31, v52
	s_nop 0
	v_addc_co_u32_e32 v55, vcc, 0, v51, vcc
	v_lshl_add_u64 v[252:253], v[252:253], 0, s[98:99]
	v_mov_b32_e32 v54, v178
	v_mov_b32_e32 v55, v179
	v_mov_b32_e32 v56, v180
	v_mov_b32_e32 v57, v181
	s_and_b64 vcc, exec, s[6:7]
	v_lshlrev_b32_e32 v60, 16, v55
	v_and_b32_e32 v61, 0xffff0000, v55
	v_lshlrev_b32_e32 v55, 16, v56
	v_mul_f32_e32 v55, 0xbfb8aa3b, v55
	v_exp_f32_e32 v55, v55
	v_lshlrev_b32_e32 v58, 16, v54
	v_and_b32_e32 v59, 0xffff0000, v54
	v_and_b32_e32 v62, 0xffff0000, v56
	v_add_f32_e32 v55, 1.0, v55
	v_mul_f32_e32 v54, 0xbfb8aa3b, v58
	v_rcp_f32_e32 v56, v55
	v_mul_f32_e32 v55, 0xbfb8aa3b, v59
	v_exp_f32_e32 v54, v54
	v_exp_f32_e32 v55, v55
	v_lshlrev_b32_e32 v63, 16, v57
	v_mul_f32_e32 v59, 0xbfb8aa3b, v63
	v_add_f32_e32 v54, 1.0, v54
	v_add_f32_e32 v55, 1.0, v55
	v_exp_f32_e32 v59, v59
	v_rcp_f32_e32 v54, v54
	v_rcp_f32_e32 v55, v55
	v_and_b32_e32 v64, 0xffff0000, v57
	v_add_f32_e32 v59, 1.0, v59
	v_mul_f32_e32 v57, 0xbfb8aa3b, v62
	v_mul_f32_e32 v58, 0xbfb8aa3b, v60
	v_rcp_f32_e32 v60, v59
	v_mul_f32_e32 v59, 0xbfb8aa3b, v61
	v_pk_mul_f32 v[46:47], v[46:47], v[54:55]
	v_mul_f32_e32 v54, 0xbfb8aa3b, v64
	v_exp_f32_e32 v57, v57
	v_exp_f32_e32 v58, v58
	v_exp_f32_e32 v59, v59
	v_exp_f32_e32 v54, v54
	v_add_f32_e32 v57, 1.0, v57
	v_add_f32_e32 v58, 1.0, v58
	v_add_f32_e32 v59, 1.0, v59
	v_add_f32_e32 v54, 1.0, v54
	v_rcp_f32_e32 v57, v57
	v_rcp_f32_e32 v58, v58
	v_rcp_f32_e32 v59, v59
	v_rcp_f32_e32 v61, v54
	v_lshlrev_b64 v[54:55], 12, v[52:53]
	v_lshl_add_u64 v[54:55], s[16:17], 0, v[54:55]
	v_pk_mul_f32 v[48:49], v[48:49], v[58:59]
	v_pk_mul_f32 v[44:45], v[44:45], v[60:61]
	v_pk_mul_f32 v[42:43], v[42:43], v[56:57]
	v_lshl_add_u64 v[54:55], v[140:141], 2, v[54:55]
	s_cbranch_vccnz .LBB0_178
	global_load_dwordx4 v[56:59], v[252:253], off
	global_load_dwordx4 v[60:63], v[252:253], off offset:1024
	s_waitcnt vmcnt(0)
	v_pk_add_f32 v[48:49], v[48:49], v[58:59]
	v_pk_add_f32 v[46:47], v[46:47], v[56:57]
	v_pk_add_f32 v[44:45], v[44:45], v[62:63]
	v_pk_add_f32 v[42:43], v[42:43], v[60:61]

; __device__ __forceinline__ unsigned cvt_pk_bf16(float lo, float hi) { unsigned r; asm("v_cvt_pk_bf16_f32 %0, %1, %2" : "=v"(r) : "v"(lo), "v"(hi)); return r; }
; __device__ __forceinline__ float sigm(float x) { return rcpf_(1.f + __expf(-x)); }
; __device__ __forceinline__ void unpack8(u32x4 w, float* e) { e[0] = lo_bf(w.x); e[1] = hi_bf(w.x); e[2] = lo_bf(w.y); e[3] = hi_bf(w.y); e[4] = lo_bf(w.z); e[5] = hi_bf(w.z); e[6] = lo_bf(w.w); e[7] = hi_bf(w.w); }
;     __device__ __forceinline__ void operator()(const f32x4 (&acc)[2][2][4][2], const Unit& u, int wr, int wc, int fr, int fq) const {
;     ...
;                     const int col = colt + bj * 128;
;                     const u32x4 gw = *(const u32x4*)(P + (size_t)row * NIN + C_GM + u.z * 1024 + col);
;                     float gt[8]; unpack8(gw, gt);
;                     f32x4 v0 = acc[ai][bj][m][0], v1 = acc[ai][bj][m][1];
; #pragma unroll
;                     for (int j = 0; j < 4; ++j) { v0[j] *= sigm(gt[j]); v1[j] *= sigm(gt[4 + j]); }
;                     float* tp = tmp + (size_t)row * 1024 + col;
;                     if (u.z > 0) { v0 += *(const f32x4*)tp; v1 += *(const f32x4*)(tp + 4); }
;                     if (u.z < 2) { *(f32x4*)tp = v0; *(f32x4*)(tp + 4) = v1; }
;                     else { u32x4 w; w.x = cvt_pk_bf16(v0[0], v0[1]); w.y = cvt_pk_bf16(v0[2], v0[3]); w.z = cvt_pk_bf16(v1[0], v1[1]); w.w = cvt_pk_bf16(v1[2], v1[3]);
;                         *(u32x4*)(merged + (size_t)row * 1024 + col) = w; }
.LBB0_180:
	s_andn2_b64 vcc, exec, s[44:45]
	s_cbranch_vccnz .LBB0_182
	global_store_dwordx4 v[252:253], v[46:49], off
	global_store_dwordx4 v[252:253], v[42:45], off offset:1024
.LBB0_182:
	s_mov_b64 s[44:45], 0x4000
	s_nop 0
	v_lshl_add_u64 v[42:43], v[50:51], 0, s[44:45]
	v_lshl_add_u64 v[252:253], v[252:253], 0, s[98:99]
	v_mov_b32_e32 v42, v230
	v_mov_b32_e32 v43, v231
	v_mov_b32_e32 v44, v232
	v_mov_b32_e32 v45, v233
	s_and_b64 vcc, exec, s[6:7]
	v_lshlrev_b32_e32 v46, 16, v42
	v_and_b32_e32 v42, 0xffff0000, v42
	v_lshlrev_b32_e32 v47, 16, v43
	v_and_b32_e32 v43, 0xffff0000, v43
	v_lshlrev_b32_e32 v48, 16, v44
	v_and_b32_e32 v44, 0xffff0000, v44
	v_lshlrev_b32_e32 v49, 16, v45
	v_and_b32_e32 v45, 0xffff0000, v45
	v_mul_f32_e32 v46, 0xbfb8aa3b, v46
	v_mul_f32_e32 v48, 0xbfb8aa3b, v48
	v_mul_f32_e32 v42, 0xbfb8aa3b, v42
	v_mul_f32_e32 v44, 0xbfb8aa3b, v44
	v_mul_f32_e32 v47, 0xbfb8aa3b, v47
	v_mul_f32_e32 v49, 0xbfb8aa3b, v49
	v_mul_f32_e32 v43, 0xbfb8aa3b, v43
	v_mul_f32_e32 v45, 0xbfb8aa3b, v45
	v_exp_f32_e32 v46, v46
	v_exp_f32_e32 v48, v48
	v_exp_f32_e32 v42, v42
	v_exp_f32_e32 v44, v44
	v_exp_f32_e32 v47, v47
	v_exp_f32_e32 v49, v49
	v_exp_f32_e32 v43, v43
	v_exp_f32_e32 v45, v45
	v_add_f32_e32 v46, 1.0, v46
	v_add_f32_e32 v48, 1.0, v48
	v_add_f32_e32 v50, 1.0, v42
	v_add_f32_e32 v51, 1.0, v44
	v_add_f32_e32 v47, 1.0, v47
	v_add_f32_e32 v49, 1.0, v49
	v_add_f32_e32 v56, 1.0, v43
	v_add_f32_e32 v45, 1.0, v45
	v_rcp_f32_e32 v42, v46
	v_rcp_f32_e32 v44, v48
	v_rcp_f32_e32 v43, v50
	v_rcp_f32_e32 v46, v47
	v_rcp_f32_e32 v47, v56
	v_rcp_f32_e32 v48, v49
	v_rcp_f32_e32 v49, v45
	v_rcp_f32_e32 v45, v51
	v_pk_mul_f32 v[40:41], v[40:41], v[46:47]
	v_pk_mul_f32 v[38:39], v[38:39], v[42:43]
	v_pk_mul_f32 v[36:37], v[36:37], v[48:49]
	v_pk_mul_f32 v[34:35], v[34:35], v[44:45]
	s_cbranch_vccnz .LBB0_184
	global_load_dwordx4 v[42:45], v[252:253], off
	global_load_dwordx4 v[46:49], v[252:253], off offset:1024
	s_waitcnt vmcnt(0)
	v_pk_add_f32 v[40:41], v[40:41], v[44:45]
	v_pk_add_f32 v[38:39], v[38:39], v[42:43]
	v_pk_add_f32 v[36:37], v[36:37], v[48:49]
	v_pk_add_f32 v[34:35], v[34:35], v[46:47]

; __device__ __forceinline__ unsigned cvt_pk_bf16(float lo, float hi) { unsigned r; asm("v_cvt_pk_bf16_f32 %0, %1, %2" : "=v"(r) : "v"(lo), "v"(hi)); return r; }
; __device__ __forceinline__ float sigm(float x) { return rcpf_(1.f + __expf(-x)); }
; __device__ __forceinline__ void unpack8(u32x4 w, float* e) { e[0] = lo_bf(w.x); e[1] = hi_bf(w.x); e[2] = lo_bf(w.y); e[3] = hi_bf(w.y); e[4] = lo_bf(w.z); e[5] = hi_bf(w.z); e[6] = lo_bf(w.w); e[7] = hi_bf(w.w); }
;     __device__ __forceinline__ void operator()(const f32x4 (&acc)[2][2][4][2], const Unit& u, int wr, int wc, int fr, int fq) const {
;     ...
;                 const int row = row0 + ai * 128 + m * 16;
;     ...
;                     const int col = colt + bj * 128;
;                     const u32x4 gw = *(const u32x4*)(P + (size_t)row * NIN + C_GM + u.z * 1024 + col);
;                     float gt[8]; unpack8(gw, gt);
;                     f32x4 v0 = acc[ai][bj][m][0], v1 = acc[ai][bj][m][1];
; #pragma unroll
;                     for (int j = 0; j < 4; ++j) { v0[j] *= sigm(gt[j]); v1[j] *= sigm(gt[4 + j]); }
;                     float* tp = tmp + (size_t)row * 1024 + col;
;                     if (u.z > 0) { v0 += *(const f32x4*)tp; v1 += *(const f32x4*)(tp + 4); }
;                     if (u.z < 2) { *(f32x4*)tp = v0; *(f32x4*)(tp + 4) = v1; }
;                     else { u32x4 w; w.x = cvt_pk_bf16(v0[0], v0[1]); w.y = cvt_pk_bf16(v0[2], v0[3]); w.z = cvt_pk_bf16(v1[0], v1[1]); w.w = cvt_pk_bf16(v1[2], v1[3]);
;                         *(u32x4*)(merged + (size_t)row * 1024 + col) = w; }
.LBB0_186:
	s_andn2_b64 vcc, exec, s[44:45]
	s_cbranch_vccnz .LBB0_188
	global_store_dwordx4 v[252:253], v[38:41], off
	global_store_dwordx4 v[252:253], v[34:37], off offset:1024
.LBB0_188:
	s_nop 1
	v_add_u32_e32 v36, 0xa0, v142
	v_mov_b64_e32 v[34:35], s[12:13]
	v_mad_i64_i32 v[34:35], s[44:45], v36, s43, v[34:35]
	v_lshl_add_u64 v[34:35], s[38:39], 1, v[34:35]
	v_lshl_add_u64 v[34:35], v[140:141], 1, v[34:35]
	v_add_co_u32_e32 v38, vcc, 0x4000, v34
	v_ashrrev_i32_e32 v37, 31, v36
	s_nop 0
	v_addc_co_u32_e32 v39, vcc, 0, v35, vcc
	v_lshl_add_u64 v[252:253], v[252:253], 0, s[98:99]
	v_mov_b32_e32 v38, v188
	v_mov_b32_e32 v39, v189
	v_mov_b32_e32 v40, v190
	v_mov_b32_e32 v41, v191
	s_and_b64 vcc, exec, s[6:7]
	v_lshlrev_b32_e32 v44, 16, v39
	v_and_b32_e32 v45, 0xffff0000, v39
	v_lshlrev_b32_e32 v39, 16, v40
	v_mul_f32_e32 v39, 0xbfb8aa3b, v39
	v_exp_f32_e32 v39, v39
	v_lshlrev_b32_e32 v42, 16, v38
	v_and_b32_e32 v43, 0xffff0000, v38
	v_and_b32_e32 v46, 0xffff0000, v40
	v_add_f32_e32 v39, 1.0, v39
	v_mul_f32_e32 v38, 0xbfb8aa3b, v42
	v_rcp_f32_e32 v40, v39
	v_mul_f32_e32 v39, 0xbfb8aa3b, v43
	v_exp_f32_e32 v38, v38
	v_exp_f32_e32 v39, v39
	v_lshlrev_b32_e32 v47, 16, v41
	v_mul_f32_e32 v43, 0xbfb8aa3b, v47
	v_add_f32_e32 v38, 1.0, v38
	v_add_f32_e32 v39, 1.0, v39
	v_exp_f32_e32 v43, v43
	v_rcp_f32_e32 v38, v38
	v_rcp_f32_e32 v39, v39
	v_and_b32_e32 v48, 0xffff0000, v41
	v_add_f32_e32 v43, 1.0, v43
	v_mul_f32_e32 v41, 0xbfb8aa3b, v46
	v_mul_f32_e32 v42, 0xbfb8aa3b, v44
	v_rcp_f32_e32 v44, v43
	v_mul_f32_e32 v43, 0xbfb8aa3b, v45
	v_pk_mul_f32 v[30:31], v[30:31], v[38:39]
	v_mul_f32_e32 v38, 0xbfb8aa3b, v48
	v_exp_f32_e32 v41, v41
	v_exp_f32_e32 v42, v42
	v_exp_f32_e32 v43, v43
	v_exp_f32_e32 v38, v38
	v_add_f32_e32 v41, 1.0, v41
	v_add_f32_e32 v42, 1.0, v42
	v_add_f32_e32 v43, 1.0, v43
	v_add_f32_e32 v38, 1.0, v38
	v_rcp_f32_e32 v41, v41
	v_rcp_f32_e32 v42, v42
	v_rcp_f32_e32 v43, v43
	v_rcp_f32_e32 v45, v38
	v_lshlrev_b64 v[38:39], 12, v[36:37]
	v_lshl_add_u64 v[38:39], s[16:17], 0, v[38:39]
	v_pk_mul_f32 v[32:33], v[32:33], v[42:43]
	v_pk_mul_f32 v[28:29], v[28:29], v[44:45]
	v_pk_mul_f32 v[26:27], v[26:27], v[40:41]
	v_lshl_add_u64 v[38:39], v[140:141], 2, v[38:39]
	s_cbranch_vccnz .LBB0_190
	global_load_dwordx4 v[40:43], v[252:253], off
	global_load_dwordx4 v[44:47], v[252:253], off offset:1024
	s_waitcnt vmcnt(0)
	v_pk_add_f32 v[32:33], v[32:33], v[42:43]
	v_pk_add_f32 v[30:31], v[30:31], v[40:41]
	v_pk_add_f32 v[28:29], v[28:29], v[46:47]
	v_pk_add_f32 v[26:27], v[26:27], v[44:45]

; __device__ __forceinline__ unsigned cvt_pk_bf16(float lo, float hi) { unsigned r; asm("v_cvt_pk_bf16_f32 %0, %1, %2" : "=v"(r) : "v"(lo), "v"(hi)); return r; }
; __device__ __forceinline__ float sigm(float x) { return rcpf_(1.f + __expf(-x)); }
; __device__ __forceinline__ void unpack8(u32x4 w, float* e) { e[0] = lo_bf(w.x); e[1] = hi_bf(w.x); e[2] = lo_bf(w.y); e[3] = hi_bf(w.y); e[4] = lo_bf(w.z); e[5] = hi_bf(w.z); e[6] = lo_bf(w.w); e[7] = hi_bf(w.w); }
;     __device__ __forceinline__ void operator()(const f32x4 (&acc)[2][2][4][2], const Unit& u, int wr, int wc, int fr, int fq) const {
;     ...
;                     const int col = colt + bj * 128;
;                     const u32x4 gw = *(const u32x4*)(P + (size_t)row * NIN + C_GM + u.z * 1024 + col);
;                     float gt[8]; unpack8(gw, gt);
;                     f32x4 v0 = acc[ai][bj][m][0], v1 = acc[ai][bj][m][1];
; #pragma unroll
;                     for (int j = 0; j < 4; ++j) { v0[j] *= sigm(gt[j]); v1[j] *= sigm(gt[4 + j]); }
;                     float* tp = tmp + (size_t)row * 1024 + col;
;                     if (u.z > 0) { v0 += *(const f32x4*)tp; v1 += *(const f32x4*)(tp + 4); }
;                     if (u.z < 2) { *(f32x4*)tp = v0; *(f32x4*)(tp + 4) = v1; }
;                     else { u32x4 w; w.x = cvt_pk_bf16(v0[0], v0[1]); w.y = cvt_pk_bf16(v0[2], v0[3]); w.z = cvt_pk_bf16(v1[0], v1[1]); w.w = cvt_pk_bf16(v1[2], v1[3]);
;                         *(u32x4*)(merged + (size_t)row * 1024 + col) = w; }
.LBB0_192:
	s_andn2_b64 vcc, exec, s[44:45]
	s_cbranch_vccnz .LBB0_194
	global_store_dwordx4 v[252:253], v[30:33], off
	global_store_dwordx4 v[252:253], v[26:29], off offset:1024
.LBB0_194:
	s_mov_b64 s[44:45], 0x4000
	s_nop 0
	v_lshl_add_u64 v[26:27], v[34:35], 0, s[44:45]
	v_lshl_add_u64 v[252:253], v[252:253], 0, s[98:99]
	v_mov_b32_e32 v26, v248
	v_mov_b32_e32 v27, v249
	v_mov_b32_e32 v28, v250
	v_mov_b32_e32 v29, v251
	s_and_b64 vcc, exec, s[6:7]
	v_lshlrev_b32_e32 v30, 16, v26
	v_and_b32_e32 v26, 0xffff0000, v26
	v_lshlrev_b32_e32 v31, 16, v27
	v_and_b32_e32 v27, 0xffff0000, v27
	v_lshlrev_b32_e32 v32, 16, v28
	v_and_b32_e32 v28, 0xffff0000, v28
	v_lshlrev_b32_e32 v33, 16, v29
	v_and_b32_e32 v29, 0xffff0000, v29
	v_mul_f32_e32 v30, 0xbfb8aa3b, v30
	v_mul_f32_e32 v32, 0xbfb8aa3b, v32
	v_mul_f32_e32 v26, 0xbfb8aa3b, v26
	v_mul_f32_e32 v28, 0xbfb8aa3b, v28
	v_mul_f32_e32 v31, 0xbfb8aa3b, v31
	v_mul_f32_e32 v33, 0xbfb8aa3b, v33
	v_mul_f32_e32 v27, 0xbfb8aa3b, v27
	v_mul_f32_e32 v29, 0xbfb8aa3b, v29
	v_exp_f32_e32 v30, v30
	v_exp_f32_e32 v32, v32
	v_exp_f32_e32 v26, v26
	v_exp_f32_e32 v28, v28
	v_exp_f32_e32 v31, v31
	v_exp_f32_e32 v33, v33
	v_exp_f32_e32 v27, v27
	v_exp_f32_e32 v29, v29
	v_add_f32_e32 v30, 1.0, v30
	v_add_f32_e32 v32, 1.0, v32
	v_add_f32_e32 v34, 1.0, v26
	v_add_f32_e32 v35, 1.0, v28
	v_add_f32_e32 v31, 1.0, v31
	v_add_f32_e32 v33, 1.0, v33
	v_add_f32_e32 v40, 1.0, v27
	v_add_f32_e32 v29, 1.0, v29
	v_rcp_f32_e32 v26, v30
	v_rcp_f32_e32 v28, v32
	v_rcp_f32_e32 v27, v34
	v_rcp_f32_e32 v30, v31
	v_rcp_f32_e32 v31, v40
	v_rcp_f32_e32 v32, v33
	v_rcp_f32_e32 v33, v29
	v_rcp_f32_e32 v29, v35
	v_pk_mul_f32 v[24:25], v[24:25], v[30:31]
	v_pk_mul_f32 v[22:23], v[22:23], v[26:27]
	v_pk_mul_f32 v[20:21], v[20:21], v[32:33]
	v_pk_mul_f32 v[18:19], v[18:19], v[28:29]
	s_cbranch_vccnz .LBB0_196
	global_load_dwordx4 v[26:29], v[252:253], off
	global_load_dwordx4 v[30:33], v[252:253], off offset:1024
	s_waitcnt vmcnt(0)
	v_pk_add_f32 v[24:25], v[24:25], v[28:29]
	v_pk_add_f32 v[22:23], v[22:23], v[26:27]
	v_pk_add_f32 v[20:21], v[20:21], v[32:33]
	v_pk_add_f32 v[18:19], v[18:19], v[30:31]

; __device__ __forceinline__ unsigned cvt_pk_bf16(float lo, float hi) { unsigned r; asm("v_cvt_pk_bf16_f32 %0, %1, %2" : "=v"(r) : "v"(lo), "v"(hi)); return r; }
; __device__ __forceinline__ float sigm(float x) { return rcpf_(1.f + __expf(-x)); }
; __device__ __forceinline__ void unpack8(u32x4 w, float* e) { e[0] = lo_bf(w.x); e[1] = hi_bf(w.x); e[2] = lo_bf(w.y); e[3] = hi_bf(w.y); e[4] = lo_bf(w.z); e[5] = hi_bf(w.z); e[6] = lo_bf(w.w); e[7] = hi_bf(w.w); }
;     __device__ __forceinline__ void operator()(const f32x4 (&acc)[2][2][4][2], const Unit& u, int wr, int wc, int fr, int fq) const {
;     ...
;                 const int row = row0 + ai * 128 + m * 16;
;     ...
;                     const int col = colt + bj * 128;
;                     const u32x4 gw = *(const u32x4*)(P + (size_t)row * NIN + C_GM + u.z * 1024 + col);
;                     float gt[8]; unpack8(gw, gt);
;                     f32x4 v0 = acc[ai][bj][m][0], v1 = acc[ai][bj][m][1];
; #pragma unroll
;                     for (int j = 0; j < 4; ++j) { v0[j] *= sigm(gt[j]); v1[j] *= sigm(gt[4 + j]); }
;                     float* tp = tmp + (size_t)row * 1024 + col;
;                     if (u.z > 0) { v0 += *(const f32x4*)tp; v1 += *(const f32x4*)(tp + 4); }
;                     if (u.z < 2) { *(f32x4*)tp = v0; *(f32x4*)(tp + 4) = v1; }
;                     else { u32x4 w; w.x = cvt_pk_bf16(v0[0], v0[1]); w.y = cvt_pk_bf16(v0[2], v0[3]); w.z = cvt_pk_bf16(v1[0], v1[1]); w.w = cvt_pk_bf16(v1[2], v1[3]);
;                         *(u32x4*)(merged + (size_t)row * 1024 + col) = w; }
.LBB0_198:
	s_andn2_b64 vcc, exec, s[44:45]
	s_cbranch_vccnz .LBB0_200
	global_store_dwordx4 v[252:253], v[22:25], off
	global_store_dwordx4 v[252:253], v[18:21], off offset:1024
.LBB0_200:
	s_nop 1
	v_add_u32_e32 v20, 0xb0, v142
	v_mov_b64_e32 v[18:19], s[12:13]
	v_mad_i64_i32 v[18:19], s[44:45], v20, s43, v[18:19]
	v_lshl_add_u64 v[18:19], s[38:39], 1, v[18:19]
	v_lshl_add_u64 v[18:19], v[140:141], 1, v[18:19]
	v_add_co_u32_e32 v22, vcc, 0x4000, v18
	v_ashrrev_i32_e32 v21, 31, v20
	s_nop 0
	v_addc_co_u32_e32 v23, vcc, 0, v19, vcc
	v_lshl_add_u64 v[252:253], v[252:253], 0, s[98:99]
	v_mov_b32_e32 v22, v192
	v_mov_b32_e32 v23, v193
	v_mov_b32_e32 v24, v194
	v_mov_b32_e32 v25, v195
	s_and_b64 vcc, exec, s[6:7]
	v_lshlrev_b32_e32 v28, 16, v23
	v_and_b32_e32 v29, 0xffff0000, v23
	v_lshlrev_b32_e32 v23, 16, v24
	v_mul_f32_e32 v23, 0xbfb8aa3b, v23
	v_exp_f32_e32 v23, v23
	v_lshlrev_b32_e32 v26, 16, v22
	v_and_b32_e32 v27, 0xffff0000, v22
	v_and_b32_e32 v30, 0xffff0000, v24
	v_add_f32_e32 v23, 1.0, v23
	v_mul_f32_e32 v22, 0xbfb8aa3b, v26
	v_rcp_f32_e32 v24, v23
	v_mul_f32_e32 v23, 0xbfb8aa3b, v27
	v_exp_f32_e32 v22, v22
	v_exp_f32_e32 v23, v23
	v_lshlrev_b32_e32 v31, 16, v25
	v_mul_f32_e32 v27, 0xbfb8aa3b, v31
	v_add_f32_e32 v22, 1.0, v22
	v_add_f32_e32 v23, 1.0, v23
	v_exp_f32_e32 v27, v27
	v_rcp_f32_e32 v22, v22
	v_rcp_f32_e32 v23, v23
	v_and_b32_e32 v32, 0xffff0000, v25
	v_add_f32_e32 v27, 1.0, v27
	v_mul_f32_e32 v25, 0xbfb8aa3b, v30
	v_mul_f32_e32 v26, 0xbfb8aa3b, v28
	v_rcp_f32_e32 v28, v27
	v_mul_f32_e32 v27, 0xbfb8aa3b, v29
	v_pk_mul_f32 v[14:15], v[14:15], v[22:23]
	v_mul_f32_e32 v22, 0xbfb8aa3b, v32
	v_exp_f32_e32 v25, v25
	v_exp_f32_e32 v26, v26
	v_exp_f32_e32 v27, v27
	v_exp_f32_e32 v22, v22
	v_add_f32_e32 v25, 1.0, v25
	v_add_f32_e32 v26, 1.0, v26
	v_add_f32_e32 v27, 1.0, v27
	v_add_f32_e32 v22, 1.0, v22
	v_rcp_f32_e32 v25, v25
	v_rcp_f32_e32 v26, v26
	v_rcp_f32_e32 v27, v27
	v_rcp_f32_e32 v29, v22
	v_lshlrev_b64 v[22:23], 12, v[20:21]
	v_lshl_add_u64 v[22:23], s[16:17], 0, v[22:23]
	v_pk_mul_f32 v[16:17], v[16:17], v[26:27]
	v_pk_mul_f32 v[12:13], v[12:13], v[28:29]
	v_pk_mul_f32 v[10:11], v[10:11], v[24:25]
	v_lshl_add_u64 v[22:23], v[140:141], 2, v[22:23]
	s_cbranch_vccnz .LBB0_202
	global_load_dwordx4 v[24:27], v[252:253], off
	global_load_dwordx4 v[28:31], v[252:253], off offset:1024
	s_waitcnt vmcnt(0)
	v_pk_add_f32 v[16:17], v[16:17], v[26:27]
	v_pk_add_f32 v[14:15], v[14:15], v[24:25]
	v_pk_add_f32 v[12:13], v[12:13], v[30:31]
	v_pk_add_f32 v[10:11], v[10:11], v[28:29]

; __device__ __forceinline__ unsigned cvt_pk_bf16(float lo, float hi) { unsigned r; asm("v_cvt_pk_bf16_f32 %0, %1, %2" : "=v"(r) : "v"(lo), "v"(hi)); return r; }
; __device__ __forceinline__ float sigm(float x) { return rcpf_(1.f + __expf(-x)); }
; __device__ __forceinline__ void unpack8(u32x4 w, float* e) { e[0] = lo_bf(w.x); e[1] = hi_bf(w.x); e[2] = lo_bf(w.y); e[3] = hi_bf(w.y); e[4] = lo_bf(w.z); e[5] = hi_bf(w.z); e[6] = lo_bf(w.w); e[7] = hi_bf(w.w); }
;     __device__ __forceinline__ void operator()(const f32x4 (&acc)[2][2][4][2], const Unit& u, int wr, int wc, int fr, int fq) const {
;     ...
;                     const int col = colt + bj * 128;
;                     const u32x4 gw = *(const u32x4*)(P + (size_t)row * NIN + C_GM + u.z * 1024 + col);
;                     float gt[8]; unpack8(gw, gt);
;                     f32x4 v0 = acc[ai][bj][m][0], v1 = acc[ai][bj][m][1];
; #pragma unroll
;                     for (int j = 0; j < 4; ++j) { v0[j] *= sigm(gt[j]); v1[j] *= sigm(gt[4 + j]); }
;                     float* tp = tmp + (size_t)row * 1024 + col;
;                     if (u.z > 0) { v0 += *(const f32x4*)tp; v1 += *(const f32x4*)(tp + 4); }
;                     if (u.z < 2) { *(f32x4*)tp = v0; *(f32x4*)(tp + 4) = v1; }
;                     else { u32x4 w; w.x = cvt_pk_bf16(v0[0], v0[1]); w.y = cvt_pk_bf16(v0[2], v0[3]); w.z = cvt_pk_bf16(v1[0], v1[1]); w.w = cvt_pk_bf16(v1[2], v1[3]);
;                         *(u32x4*)(merged + (size_t)row * 1024 + col) = w; }
.LBB0_204:
	s_andn2_b64 vcc, exec, s[38:39]
	s_cbranch_vccnz .LBB0_206
	global_store_dwordx4 v[252:253], v[14:17], off
	global_store_dwordx4 v[252:253], v[10:13], off offset:1024
.LBB0_206:
	s_mov_b64 s[38:39], 0x4000
	s_nop 0
	v_lshl_add_u64 v[10:11], v[18:19], 0, s[38:39]
	v_lshl_add_u64 v[252:253], v[252:253], 0, s[98:99]
	global_load_dwordx4 v[10:13], v[10:11], off offset:256
	s_and_b64 vcc, exec, s[6:7]
	s_waitcnt vmcnt(0)
	v_lshlrev_b32_e32 v14, 16, v10
	v_and_b32_e32 v10, 0xffff0000, v10
	v_lshlrev_b32_e32 v15, 16, v11
	v_and_b32_e32 v11, 0xffff0000, v11
	v_lshlrev_b32_e32 v16, 16, v12
	v_and_b32_e32 v12, 0xffff0000, v12
	v_lshlrev_b32_e32 v17, 16, v13
	v_and_b32_e32 v13, 0xffff0000, v13
	v_mul_f32_e32 v14, 0xbfb8aa3b, v14
	v_mul_f32_e32 v16, 0xbfb8aa3b, v16
	v_mul_f32_e32 v10, 0xbfb8aa3b, v10
	v_mul_f32_e32 v12, 0xbfb8aa3b, v12
	v_mul_f32_e32 v15, 0xbfb8aa3b, v15
	v_mul_f32_e32 v17, 0xbfb8aa3b, v17
	v_mul_f32_e32 v11, 0xbfb8aa3b, v11
	v_mul_f32_e32 v13, 0xbfb8aa3b, v13
	v_exp_f32_e32 v14, v14
	v_exp_f32_e32 v16, v16
	v_exp_f32_e32 v10, v10
	v_exp_f32_e32 v12, v12
	v_exp_f32_e32 v15, v15
	v_exp_f32_e32 v17, v17
	v_exp_f32_e32 v11, v11
	v_exp_f32_e32 v13, v13
	v_add_f32_e32 v14, 1.0, v14
	v_add_f32_e32 v16, 1.0, v16
	v_add_f32_e32 v18, 1.0, v10
	v_add_f32_e32 v19, 1.0, v12
	v_add_f32_e32 v15, 1.0, v15
	v_add_f32_e32 v17, 1.0, v17
	v_add_f32_e32 v24, 1.0, v11
	v_add_f32_e32 v13, 1.0, v13
	v_rcp_f32_e32 v10, v14
	v_rcp_f32_e32 v12, v16
	v_rcp_f32_e32 v11, v18
	v_rcp_f32_e32 v14, v15
	v_rcp_f32_e32 v15, v24
	v_rcp_f32_e32 v16, v17
	v_rcp_f32_e32 v17, v13
	v_rcp_f32_e32 v13, v19
	v_pk_mul_f32 v[8:9], v[8:9], v[14:15]
	v_pk_mul_f32 v[6:7], v[6:7], v[10:11]
	v_pk_mul_f32 v[2:3], v[2:3], v[16:17]
	v_pk_mul_f32 v[0:1], v[0:1], v[12:13]
	s_cbranch_vccnz .LBB0_208
	global_load_dwordx4 v[10:13], v[252:253], off
	global_load_dwordx4 v[14:17], v[252:253], off offset:1024
	s_waitcnt vmcnt(0)
	v_pk_add_f32 v[8:9], v[8:9], v[12:13]
	v_pk_add_f32 v[6:7], v[6:7], v[10:11]
	v_pk_add_f32 v[2:3], v[2:3], v[16:17]
	v_pk_add_f32 v[0:1], v[0:1], v[14:15]

;     __device__ __forceinline__ void operator()(const f32x4 (&acc)[2][2][4][2], const Unit& u, int wr, int wc, int fr, int fq) const {
;     ...
;                     if (u.z < 2) { *(f32x4*)tp = v0; *(f32x4*)(tp + 4) = v1; }
.LBB0_210:
	s_andn2_b64 vcc, exec, s[6:7]
	s_cbranch_vccnz .LBB0_102
	global_store_dwordx4 v[252:253], v[6:9], off
	global_store_dwordx4 v[252:253], v[0:3], off offset:1024
	s_branch .LBB0_102
